# v130 + GDN scan start delayed by two s_sleep (snapshots written later stay cache resident for phase 3b)
# baseline (speedup 1.0000x reference)
.LBB0_905:
	s_andn2_b64 vcc, exec, s[0:1]
	s_cbranch_vccnz .LBB0_931
	s_sleep 127
	s_sleep 64
	v_mov_b32_e32 v185, v181
	s_movk_i32 s0, 0x3c0
	v_ashrrev_i32_e32 v167, 6, v185
	v_lshlrev_b32_e32 v192, 10, v167
	v_lshlrev_b32_e32 v0, 6, v185
	v_and_or_b32 v0, v0, s0, v192
	v_lshrrev_b32_e32 v2, 1, v185
	v_ashrrev_i32_e32 v1, 31, v0
	v_and_b32_e32 v168, 24, v2
	v_lshl_add_u64 v[0:1], v[0:1], 1, s[20:21]
	s_waitcnt vmcnt(16)
	v_lshlrev_b32_e32 v160, 1, v168
	v_mov_b32_e32 v161, 0
	v_and_b32_e32 v166, 63, v185
	v_lshl_add_u64 v[0:1], v[0:1], 0, v[160:161]
	s_mov_b64 s[4:5], 0x11048000
	v_lshl_add_u64 v[176:177], v[0:1], 0, s[4:5]
	v_lshl_or_b32 v0, v166, 4, v192
	v_ashrrev_i32_e32 v1, 31, v0
	v_lshlrev_b64 v[162:163], 1, v[0:1]
	v_and_b32_e32 v206, 31, v166
	v_lshlrev_b32_e32 v206, 5, v206
	v_lshrrev_b32_e32 v207, 5, v166
	v_lshl_or_b32 v206, v207, 4, v206
	v_lshl_add_u32 v206, v192, 1, v206
	v_mov_b32_e32 v207, 0
	s_mov_b32 s1, 0
	v_lshl_add_u64 v[164:165], s[20:21], 0, v[162:163]
	s_mov_b64 s[4:5], 0x13148000
	s_lshl_b32 s0, s2, 19
	v_lshl_add_u64 v[178:179], v[164:165], 0, s[4:5]
	s_lshl_b64 s[4:5], s[0:1], 1
	v_lshl_add_u64 v[8:9], v[176:177], 0, s[4:5]
	v_lshl_add_u64 v[16:17], v[178:179], 0, s[4:5]
	s_or_b32 s4, s0, 0x1000
	s_mov_b32 s5, s1
	s_lshl_b64 s[4:5], s[4:5], 1
	v_lshl_add_u64 v[24:25], v[176:177], 0, s[4:5]
	v_lshl_add_u64 v[32:33], v[178:179], 0, s[4:5]
	s_or_b32 s4, s0, 0x2000
	s_mov_b32 s5, s1
	s_lshl_b64 s[4:5], s[4:5], 1
	v_lshl_add_u64 v[40:41], v[176:177], 0, s[4:5]
	v_lshl_add_u64 v[48:49], v[178:179], 0, s[4:5]
	s_or_b32 s4, s0, 0x3000
	s_mov_b32 s5, s1
	s_lshl_b64 s[4:5], s[4:5], 1
	v_lshl_add_u64 v[56:57], v[176:177], 0, s[4:5]
	v_lshl_add_u64 v[64:65], v[178:179], 0, s[4:5]
	s_or_b32 s4, s0, 0x4000
	s_mov_b32 s5, s1
	s_lshl_b64 s[4:5], s[4:5], 1
	v_lshl_add_u64 v[72:73], v[176:177], 0, s[4:5]
	v_lshl_add_u64 v[80:81], v[178:179], 0, s[4:5]
	s_or_b32 s4, s0, 0x5000
	s_mov_b32 s5, s1
	s_lshl_b64 s[4:5], s[4:5], 1
	v_lshl_add_u64 v[88:89], v[176:177], 0, s[4:5]
	v_lshl_add_u64 v[96:97], v[178:179], 0, s[4:5]
	s_or_b32 s4, s0, 0x6000
	s_mov_b32 s5, s1
	s_lshl_b64 s[4:5], s[4:5], 1
	v_lshl_add_u64 v[104:105], v[176:177], 0, s[4:5]
	v_lshl_add_u64 v[108:109], v[178:179], 0, s[4:5]
	s_or_b32 s4, s0, 0x7000
	s_mov_b32 s5, s1
	s_lshl_b64 s[4:5], s[4:5], 1
	v_lshl_add_u64 v[116:117], v[176:177], 0, s[4:5]
	v_lshl_add_u64 v[124:125], v[178:179], 0, s[4:5]
	s_or_b32 s4, s0, 0x8000
	s_mov_b32 s5, s1
	s_lshl_b64 s[4:5], s[4:5], 1
	v_lshl_add_u64 v[132:133], v[176:177], 0, s[4:5]
	v_lshl_add_u64 v[140:141], v[178:179], 0, s[4:5]
	s_or_b32 s4, s0, 0x9000
	s_mov_b32 s5, s1
	s_lshl_b64 s[4:5], s[4:5], 1
	v_lshl_add_u64 v[148:149], v[176:177], 0, s[4:5]
	v_lshl_add_u64 v[156:157], v[178:179], 0, s[4:5]
	s_barrier
	global_load_dwordx4 v[0:3], v[8:9], off
	global_load_dwordx4 v[4:7], v[8:9], off offset:64
	s_nop 0
	global_load_dwordx4 v[8:11], v[16:17], off offset:16
	global_load_dwordx4 v[12:15], v[16:17], off
	s_nop 0
	global_load_dwordx4 v[16:19], v[24:25], off
	global_load_dwordx4 v[20:23], v[24:25], off offset:64
	s_nop 0
	global_load_dwordx4 v[24:27], v[32:33], off offset:16
	global_load_dwordx4 v[28:31], v[32:33], off
	s_nop 0
	global_load_dwordx4 v[32:35], v[40:41], off
	global_load_dwordx4 v[36:39], v[40:41], off offset:64
	s_nop 0
	global_load_dwordx4 v[40:43], v[48:49], off offset:16
	global_load_dwordx4 v[44:47], v[48:49], off
	s_nop 0
	global_load_dwordx4 v[48:51], v[56:57], off
	global_load_dwordx4 v[52:55], v[56:57], off offset:64
	s_nop 0
	global_load_dwordx4 v[56:59], v[64:65], off offset:16
	global_load_dwordx4 v[60:63], v[64:65], off
	s_nop 0
	global_load_dwordx4 v[64:67], v[72:73], off
	global_load_dwordx4 v[68:71], v[72:73], off offset:64
	s_nop 0
	global_load_dwordx4 v[72:75], v[80:81], off offset:16
	global_load_dwordx4 v[76:79], v[80:81], off
	s_nop 0
	global_load_dwordx4 v[80:83], v[88:89], off
	global_load_dwordx4 v[84:87], v[88:89], off offset:64
	s_nop 0
	global_load_dwordx4 v[88:91], v[96:97], off offset:16
	global_load_dwordx4 v[92:95], v[96:97], off
	s_nop 0
	global_load_dwordx4 v[96:99], v[104:105], off
	global_load_dwordx4 v[100:103], v[104:105], off offset:64
	s_nop 0
	global_load_dwordx4 v[104:107], v[108:109], off offset:16
	s_nop 0
	global_load_dwordx4 v[108:111], v[108:109], off
	s_nop 0
	global_load_dwordx4 v[112:115], v[116:117], off
	s_nop 0
	global_load_dwordx4 v[116:119], v[116:117], off offset:64
	s_nop 0
	global_load_dwordx4 v[120:123], v[124:125], off offset:16
	s_nop 0
	global_load_dwordx4 v[124:127], v[124:125], off
	s_nop 0
	global_load_dwordx4 v[128:131], v[132:133], off
	s_nop 0
	global_load_dwordx4 v[132:135], v[132:133], off offset:64
	s_nop 0
	global_load_dwordx4 v[136:139], v[140:141], off offset:16
	s_nop 0
	global_load_dwordx4 v[140:143], v[140:141], off
	s_nop 0
	global_load_dwordx4 v[144:147], v[148:149], off
	s_nop 0
	global_load_dwordx4 v[148:151], v[148:149], off offset:64
	s_nop 0
	global_load_dwordx4 v[152:155], v[156:157], off offset:16
	s_nop 0
	global_load_dwordx4 v[156:159], v[156:157], off
	s_lshl_b32 s6, s2, 7
	s_mov_b64 s[4:5], 0x17348000
	s_mov_b32 s7, s1
	v_lshl_add_u64 v[186:187], s[20:21], 0, v[206:207]
	v_lshl_add_u64 v[186:187], v[186:187], 0, s[4:5]
	s_or_b32 s4, s0, 0x13000
	s_lshl_b32 s10, s2, 20
	s_lshl_b64 s[6:7], s[6:7], 13
	v_and_b32_e32 v184, 15, v185
	v_or_b32_e32 v166, 48, v166
	s_add_u32 s6, s20, s6
	v_mul_u32_u24_e32 v169, 0x48, v184
	v_mul_u32_u24_e32 v166, 0x48, v166
	s_addc_u32 s7, s21, s7
	v_lshl_or_b32 v164, v167, 5, v168
	v_lshlrev_b32_e32 v165, 1, v169
	v_lshlrev_b32_e32 v166, 1, v166
	v_lshl_add_u64 v[188:189], s[6:7], 0, v[206:207]
	v_mov_b32_e32 v162, v161
	v_mov_b32_e32 v163, v161
	v_add_u32_e32 v193, v164, v165
	v_add_u32_e32 v194, v164, v166
	v_add_u32_e32 v195, v165, v160
	v_add_u32_e32 v196, v166, v160
	v_mov_b32_e32 v160, v161
	v_mov_b64_e32 v[174:175], v[162:163]
	v_mov_b64_e32 v[170:171], v[162:163]
	v_mov_b64_e32 v[166:167], v[162:163]
	s_mov_b64 s[6:7], 0
	s_mov_b32 s11, 0x17348000
	s_mov_b32 s12, 0x1734a000
	s_mov_b32 s13, 0x1734c000
	s_mov_b32 s14, 0x1734e000
	s_mov_b32 s15, 0x17350000
	s_mov_b32 s16, 0x17352000
	s_mov_b32 s17, 0x17354000
	s_mov_b32 s29, 0x17356000
	v_mov_b64_e32 v[172:173], v[160:161]
	v_mov_b64_e32 v[168:169], v[160:161]
	v_mov_b64_e32 v[164:165], v[160:161]
	s_mov_b32 s34, 0
	s_branch .LBB0_908
